# v20 + gate phase rr-loop loads software-pipelined one iteration ahead (first rr's loads ride with the tile's yT loads)
# speedup vs baseline: 1.0050x; 1.0050x over previous
; DI void phase_gate(const Params& p, int ch) {
;     ...
;   for (int it = blockIdx.x; it < T / 64; it += gridDim.x) {
;     const int tok0 = it * 64;
;     { int cl = tid >> 1, th = (tid & 1) * 32; const bft* s = yT + (size_t)cl * T + tok0 + th;
; #pragma unroll
;       for (int q = 0; q < 4; ++q) { u32x4 v = *(const u32x4*)(s + q * 8);
; #pragma unroll
;         for (int k = 0; k < 4; ++k) { tile[cl * 65 + th + q * 8 + 2 * k] = __uint_as_float(v[k] << 16); tile[cl * 65 + th + q * 8 + 2 * k + 1] = __uint_as_float(v[k] & 0xffff0000u); } } }
;     __syncthreads();
; #pragma unroll 1
;     for (int rr = 0; rr < 4; ++rr) { int e = tid + rr * 512; int tl = e >> 5, cg = e & 31; int tok = tok0 + tl, cc = cg * 8, c = ch * 256 + cc; int pos = tok_pos(tok), L = tok_len(tok);
;       const bft* zr = Z + (size_t)tok * 1024; u32x4 zero = {0, 0, 0, 0};
;       u32x4 xm = pos > 0 ? *(const u32x4*)(zr - 1024 + cc) : zero, x0 = *(const u32x4*)(zr + cc), xp = pos < L - 1 ? *(const u32x4*)(zr + 1024 + cc) : zero, gt = *(const u32x4*)(zr + 768 + cc);
.LBB0_1709:
	s_lshl_b32 s0, s10, 6
	s_ashr_i32 s1, s0, 31
	v_lshl_add_u64 v[28:29], s[0:1], 1, v[46:47]
	global_load_dwordx4 v[32:35], v[28:29], off offset:48
	global_load_dwordx4 v[36:39], v[28:29], off offset:32
	global_load_dwordx4 v[40:43], v[28:29], off offset:16
	global_load_dwordx4 v[58:61], v[28:29], off
	v_ashrrev_i32_e32 v218, 5, v45
	v_add_u32_e32 v220, s0, v218
	v_cmp_gt_i32_e32 vcc, s29, v220
	v_ashrrev_i32_e32 v221, 31, v220
	v_lshlrev_b64 v[222:223], 11, v[220:221]
	s_nop 0
	v_cndmask_b32_e32 v219, v152, v153, vcc
	v_and_b32_e32 v241, v219, v220
	v_lshl_add_u64 v[222:223], s[76:77], 0, v[222:223]
	v_cmp_ne_u32_e32 vcc, 0, v241
	v_lshlrev_b32_e32 v224, 1, v44
	v_mov_b32_e32 v225, 0
	v_mov_b32_e32 v228, 0
	v_mov_b32_e32 v229, 0
	v_mov_b32_e32 v230, 0
	v_mov_b32_e32 v231, 0
	v_lshl_add_u64 v[226:227], v[222:223], 0, v[224:225]
	s_and_saveexec_b64 s[8:9], vcc
	global_load_dwordx4 v[228:231], v[226:227], off offset:-2048
	s_or_b64 exec, exec, s[8:9]
	global_load_dwordx4 v[232:235], v[226:227], off
	v_cmp_ne_u32_e32 vcc, v241, v219
	v_mov_b32_e32 v236, 0
	v_mov_b32_e32 v237, 0
	v_mov_b32_e32 v238, 0
	v_mov_b32_e32 v239, 0
	s_and_saveexec_b64 s[8:9], vcc
	global_load_dwordx4 v[236:239], v[226:227], off offset:2048
	s_or_b64 exec, exec, s[8:9]
	global_load_dwordx4 v[244:247], v[226:227], off offset:1536
	s_mov_b32 s1, 0
	s_waitcnt vmcnt(0)
	v_lshlrev_b32_e32 v0, 16, v58
	v_and_b32_e32 v28, 0xffff0000, v58
	ds_write2_b32 v57, v0, v28 offset1:1
	v_lshlrev_b32_e32 v0, 16, v59
	v_and_b32_e32 v28, 0xffff0000, v59
	ds_write2_b32 v57, v0, v28 offset0:2 offset1:3
	v_lshlrev_b32_e32 v0, 16, v60
	v_and_b32_e32 v28, 0xffff0000, v60
	ds_write2_b32 v57, v0, v28 offset0:4 offset1:5
	v_lshlrev_b32_e32 v0, 16, v61
	v_and_b32_e32 v28, 0xffff0000, v61
	ds_write2_b32 v57, v0, v28 offset0:6 offset1:7
	v_lshlrev_b32_e32 v0, 16, v40
	v_and_b32_e32 v28, 0xffff0000, v40
	ds_write2_b32 v57, v0, v28 offset0:8 offset1:9
	v_lshlrev_b32_e32 v0, 16, v41
	v_and_b32_e32 v28, 0xffff0000, v41
	ds_write2_b32 v57, v0, v28 offset0:10 offset1:11
	v_lshlrev_b32_e32 v0, 16, v42
	v_and_b32_e32 v28, 0xffff0000, v42
	ds_write2_b32 v57, v0, v28 offset0:12 offset1:13
	v_lshlrev_b32_e32 v0, 16, v43
	v_and_b32_e32 v28, 0xffff0000, v43
	ds_write2_b32 v57, v0, v28 offset0:14 offset1:15
	v_lshlrev_b32_e32 v0, 16, v36
	v_and_b32_e32 v28, 0xffff0000, v36
	ds_write2_b32 v57, v0, v28 offset0:16 offset1:17
	v_lshlrev_b32_e32 v0, 16, v37
	v_and_b32_e32 v28, 0xffff0000, v37
	ds_write2_b32 v57, v0, v28 offset0:18 offset1:19
	v_lshlrev_b32_e32 v0, 16, v38
	v_and_b32_e32 v28, 0xffff0000, v38
	ds_write2_b32 v57, v0, v28 offset0:20 offset1:21
	v_lshlrev_b32_e32 v0, 16, v39
	v_and_b32_e32 v28, 0xffff0000, v39
	ds_write2_b32 v57, v0, v28 offset0:22 offset1:23
	v_lshlrev_b32_e32 v0, 16, v32
	v_and_b32_e32 v28, 0xffff0000, v32
	ds_write2_b32 v57, v0, v28 offset0:24 offset1:25
	v_lshlrev_b32_e32 v0, 16, v33
	v_and_b32_e32 v28, 0xffff0000, v33
	ds_write2_b32 v57, v0, v28 offset0:26 offset1:27
	v_lshlrev_b32_e32 v0, 16, v34
	v_and_b32_e32 v28, 0xffff0000, v34
	ds_write2_b32 v57, v0, v28 offset0:28 offset1:29
	v_lshlrev_b32_e32 v0, 16, v35
	v_and_b32_e32 v28, 0xffff0000, v35
	ds_write2_b32 v57, v0, v28 offset0:30 offset1:31
	s_waitcnt lgkmcnt(0)
	s_barrier
	s_branch .LBB0_1711
; DI unsigned pack2(float a, float b) { return (unsigned)f2bf(a) | ((unsigned)f2bf(b) << 16); }
; __device__ __forceinline__ void xcd_barrier(const XcdBarrier& b) {
;   asm volatile("s_waitcnt vmcnt(0)" ::: "memory");
;   __syncthreads();
;   if (threadIdx.x == 0) {
;     unsigned* bar = b.bar; unsigned bx = b.x; asm volatile("" : "+s"(bx));
;     __builtin_amdgcn_s_waitcnt(0);
;     unsigned nloc = b.st[0], nx = b.st[1];
;     if (nloc == 0u) { xcd_barrier_complete(bar, bx, nloc, nx); b.st[0] = nloc; b.st[1] = nx; }
; DI void phase_gate(const Params& p, int ch) {
;     ...
; #pragma unroll 1
;     for (int rr = 0; rr < 4; ++rr) { int e = tid + rr * 512; int tl = e >> 5, cg = e & 31; int tok = tok0 + tl, cc = cg * 8, c = ch * 256 + cc; int pos = tok_pos(tok), L = tok_len(tok);
;       const bft* zr = Z + (size_t)tok * 1024; u32x4 zero = {0, 0, 0, 0};
;       u32x4 xm = pos > 0 ? *(const u32x4*)(zr - 1024 + cc) : zero, x0 = *(const u32x4*)(zr + cc), xp = pos < L - 1 ? *(const u32x4*)(zr + 1024 + cc) : zero, gt = *(const u32x4*)(zr + 768 + cc);
;       float o[8];
; #pragma unroll
;       for (int i = 0; i < 8; ++i) { int sh = (i & 1) ? 0 : 16; unsigned msk = 0xffff0000u; int w = i >> 1;
;         float a = __uint_as_float((xm[w] << sh) & msk), b = __uint_as_float((x0[w] << sh) & msk), d = __uint_as_float((xp[w] << sh) & msk), g = __uint_as_float((gt[w] << sh) & msk);
;         float xc = a * w0[0][i] + b * w0[1][i] + d * w0[2][i] + b0[i];
;         o[i] = tile[(cc + i) * 65 + tl] * xc * g; }
;       u32x4 w = {pack2(o[0], o[1]), pack2(o[2], o[3]), pack2(o[4], o[5]), pack2(o[6], o[7])};
;       *(u32x4*)(G1 + (size_t)tok * 1024 + cc) = w; }
.LBB0_1710:
.Lgate_body:
	v_lshl_add_u32 v0, v58, 2, v56
	ds_read2_b32 v[72:73], v0 offset1:65
	ds_read2_b32 v[74:75], v0 offset0:130 offset1:195
	v_add_u32_e32 v0, 0x400, v0
	s_nop 0
	v_lshlrev_b32_e32 v65, 16, v41
	v_lshlrev_b32_e32 v64, 16, v40
	ds_read2_b32 v[76:77], v0 offset0:4 offset1:69
	ds_read2_b32 v[78:79], v0 offset0:134 offset1:199
	v_lshlrev_b32_e32 v59, 16, v37
	v_lshlrev_b32_e32 v58, 16, v36
	v_and_b32_e32 v41, 0xffff0000, v41
	v_and_b32_e32 v40, 0xffff0000, v40
	v_lshlrev_b32_e32 v71, 16, v43
	v_lshlrev_b32_e32 v70, 16, v42
	v_and_b32_e32 v43, 0xffff0000, v43
	v_and_b32_e32 v42, 0xffff0000, v42
	v_pk_mul_f32 v[64:65], v[18:19], v[64:65]
	v_lshlrev_b32_e32 v54, 16, v32
	v_lshlrev_b32_e32 v55, 16, v33
	v_and_b32_e32 v37, 0xffff0000, v37
	v_and_b32_e32 v36, 0xffff0000, v36
	v_lshlrev_b32_e32 v69, 16, v39
	v_lshlrev_b32_e32 v68, 16, v38
	v_and_b32_e32 v39, 0xffff0000, v39
	v_and_b32_e32 v38, 0xffff0000, v38
	v_pk_mul_f32 v[40:41], v[12:13], v[40:41]
	v_pk_mul_f32 v[70:71], v[26:27], v[70:71]
	v_pk_mul_f32 v[42:43], v[20:21], v[42:43]
	v_pk_fma_f32 v[58:59], v[6:7], v[58:59], v[64:65]
	v_and_b32_e32 v32, 0xffff0000, v32
	v_and_b32_e32 v33, 0xffff0000, v33
	v_lshlrev_b32_e32 v66, 16, v34
	v_and_b32_e32 v34, 0xffff0000, v34
	v_lshlrev_b32_e32 v67, 16, v35
	v_and_b32_e32 v35, 0xffff0000, v35
	v_pk_fma_f32 v[36:37], v[52:53], v[36:37], v[40:41]
	v_pk_fma_f32 v[40:41], v[14:15], v[68:69], v[70:71]
	v_pk_fma_f32 v[38:39], v[8:9], v[38:39], v[42:43]
	v_pk_fma_f32 v[42:43], v[22:23], v[54:55], v[58:59]
	v_pk_fma_f32 v[32:33], v[16:17], v[32:33], v[36:37]
	v_pk_fma_f32 v[36:37], v[30:31], v[66:67], v[40:41]
	v_pk_fma_f32 v[34:35], v[24:25], v[34:35], v[38:39]
	v_pk_add_f32 v[38:39], v[2:3], v[42:43]
	s_waitcnt lgkmcnt(3)
	v_mov_b32_e32 v40, v72
	s_waitcnt lgkmcnt(2)
	v_mov_b32_e32 v41, v74
	v_pk_add_f32 v[36:37], v[10:11], v[36:37]
	v_pk_add_f32 v[34:35], v[4:5], v[34:35]
	v_pk_mul_f32 v[38:39], v[40:41], v[38:39]
	s_waitcnt lgkmcnt(1)
	v_mov_b32_e32 v40, v76
	s_waitcnt lgkmcnt(0)
	v_mov_b32_e32 v41, v78
	v_mov_b32_e32 v78, v77
	v_pk_add_f32 v[32:33], v[50:51], v[32:33]
	v_mov_b32_e32 v74, v73
	v_pk_mul_f32 v[36:37], v[40:41], v[36:37]
	v_pk_mul_f32 v[34:35], v[34:35], v[78:79]
	v_pk_mul_f32 v[32:33], v[74:75], v[32:33]
	v_lshlrev_b64 v[28:29], 10, v[28:29]
	s_addk_i32 s1, 0x200
	v_lshl_add_u64 v[28:29], v[28:29], 1, v[48:49]
	s_cmpk_eq_i32 s1, 0x800
	s_nop 0
	v_lshlrev_b32_e32 v41, 16, v61
	v_lshlrev_b32_e32 v40, 16, v60
	v_lshlrev_b32_e32 v55, 16, v63
	v_lshlrev_b32_e32 v54, 16, v62
	v_and_b32_e32 v59, 0xffff0000, v63
	v_and_b32_e32 v58, 0xffff0000, v62
	v_and_b32_e32 v43, 0xffff0000, v61
	v_and_b32_e32 v42, 0xffff0000, v60
	v_pk_mul_f32 v[38:39], v[38:39], v[40:41]
	v_pk_mul_f32 v[36:37], v[36:37], v[54:55]
	v_pk_mul_f32 v[34:35], v[34:35], v[58:59]
	v_pk_mul_f32 v[32:33], v[32:33], v[42:43]
	v_cvt_pk_bf16_f32 v35, v37, v35
	v_cvt_pk_bf16_f32 v34, v36, v34
	v_cvt_pk_bf16_f32 v33, v39, v33
	v_cvt_pk_bf16_f32 v32, v38, v32
	global_store_dwordx4 v[28:29], v[32:35], off
	s_cbranch_scc1 .LBB0_1708
.LBB0_1711:
	v_add_u32_e32 v0, s1, v45
	v_ashrrev_i32_e32 v58, 5, v0
	v_add_u32_e32 v28, s0, v58
	v_ashrrev_i32_e32 v29, 31, v28
	s_waitcnt vmcnt(1)
	v_mov_b32_e32 v36, v228
	v_mov_b32_e32 v37, v229
	v_mov_b32_e32 v38, v230
	v_mov_b32_e32 v39, v231
	v_mov_b32_e32 v40, v232
	v_mov_b32_e32 v41, v233
	v_mov_b32_e32 v42, v234
	v_mov_b32_e32 v43, v235
	v_mov_b32_e32 v32, v236
	v_mov_b32_e32 v33, v237
	v_mov_b32_e32 v34, v238
	v_mov_b32_e32 v35, v239
	v_mov_b32_e32 v60, v244
	v_mov_b32_e32 v61, v245
	v_mov_b32_e32 v62, v246
	v_mov_b32_e32 v63, v247
	s_cmpk_eq_i32 s1, 0x600
	s_cbranch_scc1 .Lgate_nopf
	v_add_u32_e32 v218, s1, v45
	v_add_u32_e32 v218, 0x200, v218
	v_ashrrev_i32_e32 v218, 5, v218
	v_add_u32_e32 v220, s0, v218
	v_cmp_gt_i32_e32 vcc, s29, v220
	v_ashrrev_i32_e32 v221, 31, v220
	v_lshlrev_b64 v[222:223], 11, v[220:221]
	s_nop 0
	v_cndmask_b32_e32 v219, v152, v153, vcc
	v_and_b32_e32 v241, v219, v220
	v_lshl_add_u64 v[222:223], s[76:77], 0, v[222:223]
	v_cmp_ne_u32_e32 vcc, 0, v241
	v_lshlrev_b32_e32 v224, 1, v44
	v_mov_b32_e32 v225, 0
	v_mov_b32_e32 v228, 0
	v_mov_b32_e32 v229, 0
	v_mov_b32_e32 v230, 0
	v_mov_b32_e32 v231, 0
	v_lshl_add_u64 v[226:227], v[222:223], 0, v[224:225]
	s_and_saveexec_b64 s[8:9], vcc
	global_load_dwordx4 v[228:231], v[226:227], off offset:-2048
	s_or_b64 exec, exec, s[8:9]
	global_load_dwordx4 v[232:235], v[226:227], off
	v_cmp_ne_u32_e32 vcc, v241, v219
	v_mov_b32_e32 v236, 0
	v_mov_b32_e32 v237, 0
	v_mov_b32_e32 v238, 0
	v_mov_b32_e32 v239, 0
	s_and_saveexec_b64 s[8:9], vcc
	global_load_dwordx4 v[236:239], v[226:227], off offset:2048
	s_or_b64 exec, exec, s[8:9]
	global_load_dwordx4 v[244:247], v[226:227], off offset:1536
.Lgate_nopf:
	s_branch .Lgate_body
.LBB0_1715:
	s_waitcnt vmcnt(0)
	s_barrier
	s_mov_b64 s[0:1], exec
	v_readlane_b32 s8, v240, 0
	v_readlane_b32 s9, v240, 1
	s_and_b64 s[8:9], s[0:1], s[8:9]
	s_movk_i32 s75, 0x70
	s_mov_b64 exec, s[8:9]
	s_cbranch_execz .LBB0_1111
	v_readlane_b32 s14, v240, 4
	s_waitcnt vmcnt(0) expcnt(0) lgkmcnt(0)
	ds_read_b32 v3, v1
	ds_read_b32 v2, v1 offset:4
	s_waitcnt lgkmcnt(1)
	v_cmp_ne_u32_e32 vcc, 0, v3
	s_cbranch_vccnz .LBB0_1731
	s_mov_b32 s15, 1
	s_branch .LBB0_1719
